# v26 plus attention unit epilogue widened per strategy 7.3: 16 dwordx2 stores per lane become 8 dwordx4 via v_permlane32_swap, in-place scale and bf16 convert, block-1 normaliser moved to free v74-v79
# speedup vs baseline: 1.0110x; 1.0110x over previous
; __device__ __forceinline__ unsigned cvtpk(float lo, float hi) { f32x2_t v = {lo, hi}; bf16x2_t b = __builtin_convertvector(v, bf16x2_t); return __builtin_bit_cast(unsigned, b); }
; __device__ __forceinline__ void attn_phase(LAS unsigned char* lds, const bf16_t* Qb, const bf16_t* Kimg, const bf16_t* Vimg, bf16_t* AB, int bid, int G, int wave_k) {
;     ...
;         int lane_o = lane; asm volatile("" : "+v"(lane_o));
; #pragma unroll
;         for (int b = 0; b < 2; ++b) { const float lt = lrun[b] + __shfl_xor(lrun[b], 32), il = 1.f / lt;
;             bf16_t* orow = AB + (size_t)(qrow0 + 32 * b + (lane_o & 31)) * DM + h * VH + 4 * (lane_o >> 5);
; #pragma unroll
;             for (int g = 0; g < 4; ++g) {
;                 *(u32x2*)(orow + 8 * g) = (u32x2){cvtpk(o[b][0][4 * g] * il, o[b][0][4 * g + 1] * il), cvtpk(o[b][0][4 * g + 2] * il, o[b][0][4 * g + 3] * il)};
;                 *(u32x2*)(orow + 32 + 8 * g) = (u32x2){cvtpk(o[b][1][4 * g] * il, o[b][1][4 * g + 1] * il), cvtpk(o[b][1][4 * g + 2] * il, o[b][1][4 * g + 3] * il)}; } }
.LBB0_947:
	s_waitcnt lgkmcnt(0)
	s_barrier
	v_and_b32_e32 v66, 64, v229
	v_xor_b32_e32 v64, 32, v229
	v_add_u32_e32 v66, 64, v66
	v_mov_b32_e32 v65, v235
	v_cmp_lt_i32_e32 vcc, v64, v66
	s_lshl_b32 s0, s59, 7
	s_add_u32 s0, s40, s0
	v_cndmask_b32_e32 v64, v229, v64, vcc
	v_lshlrev_b32_e32 v69, 2, v64
	v_and_or_b32 v64, v65, 31, s60
	v_ashrrev_i32_e32 v65, 2, v65
	v_and_b32_e32 v66, -8, v65
	ds_bpermute_b32 v65, v69, v223
	s_addc_u32 s1, s41, 0
	v_ashrrev_i32_e32 v67, 31, v66
	v_lshl_add_u64 v[66:67], v[66:67], 1, s[0:1]
	s_add_i32 s26, s26, s27
	s_waitcnt lgkmcnt(0)
	v_add_f32_e32 v65, v223, v65
	v_div_scale_f32 v68, s[0:1], v65, v65, 1.0
	v_rcp_f32_e32 v70, v68
	s_cmpk_lt_i32 s26, 0x100
	v_fma_f32 v71, -v68, v70, 1.0
	v_fmac_f32_e32 v70, v71, v70
	v_div_scale_f32 v71, vcc, 1.0, v65, 1.0
	v_mul_f32_e32 v72, v71, v70
	v_fma_f32 v73, -v68, v72, v71
	v_fmac_f32_e32 v72, v73, v70
	v_fma_f32 v68, -v68, v72, v71
	v_div_fmas_f32 v68, v68, v70, v72
	v_div_fixup_f32 v68, v68, v65, 1.0
	v_ashrrev_i32_e32 v65, 31, v64
	v_lshlrev_b64 v[70:71], 11, v[64:65]
	v_lshl_add_u64 v[70:71], v[66:67], 0, v[70:71]
	ds_bpermute_b32 v74, v69, v222
	v_pk_mul_f32 v[32:33], v[32:33], v[68:69] op_sel_hi:[1,0]
	v_pk_mul_f32 v[34:35], v[34:35], v[68:69] op_sel_hi:[1,0]
	v_pk_mul_f32 v[36:37], v[36:37], v[68:69] op_sel_hi:[1,0]
	v_pk_mul_f32 v[38:39], v[38:39], v[68:69] op_sel_hi:[1,0]
	v_pk_mul_f32 v[40:41], v[40:41], v[68:69] op_sel_hi:[1,0]
	v_pk_mul_f32 v[42:43], v[42:43], v[68:69] op_sel_hi:[1,0]
	v_pk_mul_f32 v[44:45], v[44:45], v[68:69] op_sel_hi:[1,0]
	v_pk_mul_f32 v[46:47], v[46:47], v[68:69] op_sel_hi:[1,0]
	v_pk_mul_f32 v[48:49], v[48:49], v[68:69] op_sel_hi:[1,0]
	v_pk_mul_f32 v[50:51], v[50:51], v[68:69] op_sel_hi:[1,0]
	v_pk_mul_f32 v[52:53], v[52:53], v[68:69] op_sel_hi:[1,0]
	v_pk_mul_f32 v[54:55], v[54:55], v[68:69] op_sel_hi:[1,0]
	v_pk_mul_f32 v[56:57], v[56:57], v[68:69] op_sel_hi:[1,0]
	v_pk_mul_f32 v[58:59], v[58:59], v[68:69] op_sel_hi:[1,0]
	v_pk_mul_f32 v[60:61], v[60:61], v[68:69] op_sel_hi:[1,0]
	v_pk_mul_f32 v[62:63], v[62:63], v[68:69] op_sel_hi:[1,0]
	v_cvt_pk_bf16_f32 v32, v32, v33
	v_cvt_pk_bf16_f32 v33, v34, v35
	v_cvt_pk_bf16_f32 v34, v36, v37
	v_cvt_pk_bf16_f32 v35, v38, v39
	v_cvt_pk_bf16_f32 v40, v40, v41
	v_cvt_pk_bf16_f32 v41, v42, v43
	v_cvt_pk_bf16_f32 v42, v44, v45
	v_cvt_pk_bf16_f32 v43, v46, v47
	v_cvt_pk_bf16_f32 v48, v48, v49
	v_cvt_pk_bf16_f32 v49, v50, v51
	v_cvt_pk_bf16_f32 v50, v52, v53
	v_cvt_pk_bf16_f32 v51, v54, v55
	v_cvt_pk_bf16_f32 v56, v56, v57
	v_cvt_pk_bf16_f32 v57, v58, v59
	v_cvt_pk_bf16_f32 v58, v60, v61
	v_cvt_pk_bf16_f32 v59, v62, v63
	v_permlane32_swap_b32_e32 v32, v34
	v_permlane32_swap_b32_e32 v33, v35
	v_permlane32_swap_b32_e32 v40, v42
	v_permlane32_swap_b32_e32 v41, v43
	v_permlane32_swap_b32_e32 v48, v50
	v_permlane32_swap_b32_e32 v49, v51
	v_permlane32_swap_b32_e32 v56, v58
	v_permlane32_swap_b32_e32 v57, v59
	global_store_dwordx4 v[70:71], v[32:35], off offset:64
	global_store_dwordx4 v[70:71], v[40:43], off offset:96
	global_store_dwordx4 v[70:71], v[48:51], off
	global_store_dwordx4 v[70:71], v[56:59], off offset:32
	s_waitcnt lgkmcnt(0)
	v_add_f32_e32 v74, v222, v74
	v_div_scale_f32 v75, s[0:1], v74, v74, 1.0
	v_rcp_f32_e32 v76, v75
	s_nop 0
	v_fma_f32 v77, -v75, v76, 1.0
	v_fmac_f32_e32 v76, v77, v76
	v_div_scale_f32 v77, vcc, 1.0, v74, 1.0
	v_mul_f32_e32 v78, v77, v76
	v_fma_f32 v79, -v75, v78, v77
	v_fmac_f32_e32 v78, v79, v76
	v_fma_f32 v75, -v75, v78, v77
	v_div_fmas_f32 v75, v75, v76, v78
	v_or_b32_e32 v76, 32, v64
	v_div_fixup_f32 v74, v75, v74, 1.0
	v_ashrrev_i32_e32 v77, 31, v76
	v_lshlrev_b64 v[76:77], 11, v[76:77]
	v_lshl_add_u64 v[76:77], v[66:67], 0, v[76:77]
	v_pk_mul_f32 v[0:1], v[0:1], v[74:75] op_sel_hi:[1,0]
	v_pk_mul_f32 v[2:3], v[2:3], v[74:75] op_sel_hi:[1,0]
	v_pk_mul_f32 v[4:5], v[4:5], v[74:75] op_sel_hi:[1,0]
	v_pk_mul_f32 v[6:7], v[6:7], v[74:75] op_sel_hi:[1,0]
	v_pk_mul_f32 v[8:9], v[8:9], v[74:75] op_sel_hi:[1,0]
	v_pk_mul_f32 v[10:11], v[10:11], v[74:75] op_sel_hi:[1,0]
	v_pk_mul_f32 v[12:13], v[12:13], v[74:75] op_sel_hi:[1,0]
	v_pk_mul_f32 v[14:15], v[14:15], v[74:75] op_sel_hi:[1,0]
	v_pk_mul_f32 v[16:17], v[16:17], v[74:75] op_sel_hi:[1,0]
	v_pk_mul_f32 v[18:19], v[18:19], v[74:75] op_sel_hi:[1,0]
	v_pk_mul_f32 v[20:21], v[20:21], v[74:75] op_sel_hi:[1,0]
	v_pk_mul_f32 v[22:23], v[22:23], v[74:75] op_sel_hi:[1,0]
	v_pk_mul_f32 v[24:25], v[24:25], v[74:75] op_sel_hi:[1,0]
	v_pk_mul_f32 v[26:27], v[26:27], v[74:75] op_sel_hi:[1,0]
	v_pk_mul_f32 v[28:29], v[28:29], v[74:75] op_sel_hi:[1,0]
	v_pk_mul_f32 v[30:31], v[30:31], v[74:75] op_sel_hi:[1,0]
	v_cvt_pk_bf16_f32 v0, v0, v1
	v_cvt_pk_bf16_f32 v1, v2, v3
	v_cvt_pk_bf16_f32 v2, v4, v5
	v_cvt_pk_bf16_f32 v3, v6, v7
	v_cvt_pk_bf16_f32 v8, v8, v9
	v_cvt_pk_bf16_f32 v9, v10, v11
	v_cvt_pk_bf16_f32 v10, v12, v13
	v_cvt_pk_bf16_f32 v11, v14, v15
	v_cvt_pk_bf16_f32 v16, v16, v17
	v_cvt_pk_bf16_f32 v17, v18, v19
	v_cvt_pk_bf16_f32 v18, v20, v21
	v_cvt_pk_bf16_f32 v19, v22, v23
	v_cvt_pk_bf16_f32 v24, v24, v25
	v_cvt_pk_bf16_f32 v25, v26, v27
	v_cvt_pk_bf16_f32 v26, v28, v29
	v_cvt_pk_bf16_f32 v27, v30, v31
	v_permlane32_swap_b32_e32 v0, v2
	v_permlane32_swap_b32_e32 v1, v3
	v_permlane32_swap_b32_e32 v8, v10
	v_permlane32_swap_b32_e32 v9, v11
	v_permlane32_swap_b32_e32 v16, v18
	v_permlane32_swap_b32_e32 v17, v19
	v_permlane32_swap_b32_e32 v24, v26
	v_permlane32_swap_b32_e32 v25, v27
	global_store_dwordx4 v[76:77], v[0:3], off offset:64
	global_store_dwordx4 v[76:77], v[8:11], off offset:96
	global_store_dwordx4 v[76:77], v[16:19], off
	global_store_dwordx4 v[76:77], v[24:27], off offset:32
	s_cbranch_scc0 .LBB0_985
